# P1 epilogue: C tile staged in LDS and stored as whole 512-byte rows (16 dwordx4 per thread instead of 64 dword)
# baseline (speedup 1.0000x reference)
; DEVINL float sigm(float x) { return 1.f / (1.f + __expf(-x)); }
; template <int EPI, bool GATHER>
; DEVINL void gemm_tile(const Params& p, const u16* __restrict__ A, int lda, const int* __restrict__ rowidx,
;                       const u16* __restrict__ Bt, int ldb, int K, int brow, int bcol, int orow, int ocol) {
;     ...
;   const int row0 = orow + wr * 64 + fq * 4;
;   const int col0 = ocol + wc * 32 + fr;
;   const bool odd = (fr & 1) != 0;
;   const int colp = col0 - (odd ? 1 : 0);
; #pragma unroll
;   for (int ai = 0; ai < 2; ++ai)
; #pragma unroll
;     for (int m = 0; m < 4; ++m) {
;       const int rA = row0 + ai * HALF + m * 16 + (odd ? 2 : 0);
;       float gate[2] = {0.f, 0.f};
;       if (EPI == EPI_MOE2) { gate[0] = ((const float*)(ws + O_SELG))[rA]; gate[1] = ((const float*)(ws + O_SELG))[rA + 1]; }
; #pragma unroll
;       for (int bj = 0; bj < (EPI == EPI_HID ? 1 : 2); ++bj)
; #pragma unroll
;         for (int n = 0; n < 2; ++n) {
;           const int cc = bj * HALF + n * 16;
;           f32x4 v = acc[ai][bj][m][n];
;           if (EPI == EPI_HID) {
; #pragma unroll
;             for (int j = 0; j < 4; ++j) { const float a1 = acc[ai][0][m][n][j], a3 = acc[ai][1][m][n][j]; v[j] = a1 * sigm(a1) * a3; }
;           }
;           float lo[2], hi[2];
;           xchg_pairs(v, odd, lo, hi);
; #pragma unroll
;           for (int k = 0; k < 2; ++k) {
;             const unsigned row = (unsigned)(rA + k);
;             if (EPI == EPI_HID) {
;               *(unsigned*)(ws + O_HID + (row * 1024u + (unsigned)(colp + cc)) * 2u) = pk2(lo[k], hi[k]);
;             } else if (EPI == EPI_COLS) {
;               *(unsigned*)(ws + O_COLS + (row * (unsigned)NCP + (unsigned)(colp + cc)) * 2u) = pk2(lo[k], hi[k]);
.LBB0_223:
	s_or_b64 exec, exec, s[6:7]
	v_and_b32_e32 v128, 63, v189
	v_lshrrev_b32_e32 v129, 6, v189
	v_and_b32_e32 v135, 15, v128
	v_lshrrev_b32_e32 v136, 4, v128
	v_and_b32_e32 v137, 1, v135
	v_lshrrev_b32_e32 v138, 2, v129
	v_and_b32_e32 v139, 3, v129
	v_lshlrev_b32_e32 v138, 6, v138
	v_lshl_add_u32 v138, v136, 2, v138
	v_lshl_add_u32 v138, v137, 1, v138
	v_mul_u32_u24_e32 v130, 528, v138
	v_lshl_add_u32 v139, v139, 5, v135
	v_sub_u32_e32 v139, v139, v137
	v_lshl_add_u32 v130, v139, 1, v130
	v_add_u32_e32 v130, 16, v130
	v_add_u32_e32 v131, 67584, v130
	v_cmp_eq_u32_e32 vcc, 0, v137
	v_lshrrev_b32_e32 v141, 5, v189
	v_and_b32_e32 v142, 31, v189
	v_mul_u32_u24_e32 v132, 528, v141
	v_lshl_add_u32 v132, v142, 4, v132
	v_add_u32_e32 v132, 16, v132
	v_add_u32_e32 v133, 67584, v132
	v_add_u32_e32 v141, s48, v141
	s_movk_i32 s4, 0x5400
	v_mul_lo_u32 v134, v141, s4
	v_lshl_add_u32 v142, v142, 3, s78
	v_lshl_add_u32 v134, v142, 1, v134
	s_barrier
	v_cndmask_b32_e32 v143, v124, v126, vcc
	v_cndmask_b32_e32 v144, v125, v127, vcc
	v_cndmask_b32_e32 v145, v116, v118, vcc
	v_cndmask_b32_e32 v146, v117, v119, vcc
	v_mov_b32_dpp v143, v143 quad_perm:[1,0,3,2] row_mask:0xf bank_mask:0xf bound_ctrl:1
	v_mov_b32_dpp v144, v144 quad_perm:[1,0,3,2] row_mask:0xf bank_mask:0xf bound_ctrl:1
	v_mov_b32_dpp v145, v145 quad_perm:[1,0,3,2] row_mask:0xf bank_mask:0xf bound_ctrl:1
	v_mov_b32_dpp v146, v146 quad_perm:[1,0,3,2] row_mask:0xf bank_mask:0xf bound_ctrl:1
	v_cndmask_b32_e32 v124, v143, v124, vcc
	v_cndmask_b32_e32 v126, v126, v143, vcc
	v_cndmask_b32_e32 v125, v144, v125, vcc
	v_cndmask_b32_e32 v127, v127, v144, vcc
	v_cvt_pk_bf16_f32 v124, v124, v126
	v_cvt_pk_bf16_f32 v125, v125, v127
	ds_write_b32 v130, v124
	ds_write_b32 v130, v125 offset:528
	v_cndmask_b32_e32 v116, v145, v116, vcc
	v_cndmask_b32_e32 v118, v118, v145, vcc
	v_cndmask_b32_e32 v117, v146, v117, vcc
	v_cndmask_b32_e32 v119, v119, v146, vcc
	v_cvt_pk_bf16_f32 v116, v116, v118
	v_cvt_pk_bf16_f32 v117, v117, v119
	ds_write_b32 v130, v116 offset:32
	ds_write_b32 v130, v117 offset:560
	v_cndmask_b32_e32 v143, v120, v122, vcc
	v_cndmask_b32_e32 v144, v121, v123, vcc
	v_cndmask_b32_e32 v145, v112, v114, vcc
	v_cndmask_b32_e32 v146, v113, v115, vcc
	v_mov_b32_dpp v143, v143 quad_perm:[1,0,3,2] row_mask:0xf bank_mask:0xf bound_ctrl:1
	v_mov_b32_dpp v144, v144 quad_perm:[1,0,3,2] row_mask:0xf bank_mask:0xf bound_ctrl:1
	v_mov_b32_dpp v145, v145 quad_perm:[1,0,3,2] row_mask:0xf bank_mask:0xf bound_ctrl:1
	v_mov_b32_dpp v146, v146 quad_perm:[1,0,3,2] row_mask:0xf bank_mask:0xf bound_ctrl:1
	v_cndmask_b32_e32 v120, v143, v120, vcc
	v_cndmask_b32_e32 v122, v122, v143, vcc
	v_cndmask_b32_e32 v121, v144, v121, vcc
	v_cndmask_b32_e32 v123, v123, v144, vcc
	v_cvt_pk_bf16_f32 v120, v120, v122
	v_cvt_pk_bf16_f32 v121, v121, v123
	ds_write_b32 v130, v120 offset:256
	ds_write_b32 v130, v121 offset:784
	v_cndmask_b32_e32 v112, v145, v112, vcc
	v_cndmask_b32_e32 v114, v114, v145, vcc
	v_cndmask_b32_e32 v113, v146, v113, vcc
	v_cndmask_b32_e32 v115, v115, v146, vcc
	v_cvt_pk_bf16_f32 v112, v112, v114
	v_cvt_pk_bf16_f32 v113, v113, v115
	ds_write_b32 v130, v112 offset:288
	ds_write_b32 v130, v113 offset:816
	v_cndmask_b32_e32 v143, v108, v110, vcc
	v_cndmask_b32_e32 v144, v109, v111, vcc
	v_cndmask_b32_e32 v145, v100, v102, vcc
	v_cndmask_b32_e32 v146, v101, v103, vcc
	v_mov_b32_dpp v143, v143 quad_perm:[1,0,3,2] row_mask:0xf bank_mask:0xf bound_ctrl:1
	v_mov_b32_dpp v144, v144 quad_perm:[1,0,3,2] row_mask:0xf bank_mask:0xf bound_ctrl:1
	v_mov_b32_dpp v145, v145 quad_perm:[1,0,3,2] row_mask:0xf bank_mask:0xf bound_ctrl:1
	v_mov_b32_dpp v146, v146 quad_perm:[1,0,3,2] row_mask:0xf bank_mask:0xf bound_ctrl:1
	v_cndmask_b32_e32 v108, v143, v108, vcc
	v_cndmask_b32_e32 v110, v110, v143, vcc
	v_cndmask_b32_e32 v109, v144, v109, vcc
	v_cndmask_b32_e32 v111, v111, v144, vcc
	v_cvt_pk_bf16_f32 v108, v108, v110
	v_cvt_pk_bf16_f32 v109, v109, v111
	ds_write_b32 v130, v108 offset:8448
	ds_write_b32 v130, v109 offset:8976
	v_cndmask_b32_e32 v100, v145, v100, vcc
	v_cndmask_b32_e32 v102, v102, v145, vcc
	v_cndmask_b32_e32 v101, v146, v101, vcc
	v_cndmask_b32_e32 v103, v103, v146, vcc
	v_cvt_pk_bf16_f32 v100, v100, v102
	v_cvt_pk_bf16_f32 v101, v101, v103
	ds_write_b32 v130, v100 offset:8480
	ds_write_b32 v130, v101 offset:9008
	v_cndmask_b32_e32 v143, v104, v106, vcc
	v_cndmask_b32_e32 v144, v105, v107, vcc
	v_cndmask_b32_e32 v145, v96, v98, vcc
	v_cndmask_b32_e32 v146, v97, v99, vcc
	v_mov_b32_dpp v143, v143 quad_perm:[1,0,3,2] row_mask:0xf bank_mask:0xf bound_ctrl:1
	v_mov_b32_dpp v144, v144 quad_perm:[1,0,3,2] row_mask:0xf bank_mask:0xf bound_ctrl:1
	v_mov_b32_dpp v145, v145 quad_perm:[1,0,3,2] row_mask:0xf bank_mask:0xf bound_ctrl:1
	v_mov_b32_dpp v146, v146 quad_perm:[1,0,3,2] row_mask:0xf bank_mask:0xf bound_ctrl:1
	v_cndmask_b32_e32 v104, v143, v104, vcc
	v_cndmask_b32_e32 v106, v106, v143, vcc
	v_cndmask_b32_e32 v105, v144, v105, vcc
	v_cndmask_b32_e32 v107, v107, v144, vcc
	v_cvt_pk_bf16_f32 v104, v104, v106
	v_cvt_pk_bf16_f32 v105, v105, v107
	ds_write_b32 v130, v104 offset:8704
	ds_write_b32 v130, v105 offset:9232
	v_cndmask_b32_e32 v96, v145, v96, vcc
	v_cndmask_b32_e32 v98, v98, v145, vcc
	v_cndmask_b32_e32 v97, v146, v97, vcc
	v_cndmask_b32_e32 v99, v99, v146, vcc
	v_cvt_pk_bf16_f32 v96, v96, v98
	v_cvt_pk_bf16_f32 v97, v97, v99
	ds_write_b32 v130, v96 offset:8736
	ds_write_b32 v130, v97 offset:9264
	v_cndmask_b32_e32 v143, v92, v94, vcc
	v_cndmask_b32_e32 v144, v93, v95, vcc
	v_cndmask_b32_e32 v145, v84, v86, vcc
	v_cndmask_b32_e32 v146, v85, v87, vcc
	v_mov_b32_dpp v143, v143 quad_perm:[1,0,3,2] row_mask:0xf bank_mask:0xf bound_ctrl:1
; DEVINL float sigm(float x) { return 1.f / (1.f + __expf(-x)); }
; template <int EPI, bool GATHER>
; DEVINL void gemm_tile(const Params& p, const u16* __restrict__ A, int lda, const int* __restrict__ rowidx,
;                       const u16* __restrict__ Bt, int ldb, int K, int brow, int bcol, int orow, int ocol) {
;     ...
;         for (int n = 0; n < 2; ++n) {
;           const int cc = bj * HALF + n * 16;
;           f32x4 v = acc[ai][bj][m][n];
;           if (EPI == EPI_HID) {
; #pragma unroll
;             for (int j = 0; j < 4; ++j) { const float a1 = acc[ai][0][m][n][j], a3 = acc[ai][1][m][n][j]; v[j] = a1 * sigm(a1) * a3; }
;           }
;           float lo[2], hi[2];
;           xchg_pairs(v, odd, lo, hi);
; #pragma unroll
;           for (int k = 0; k < 2; ++k) {
;             const unsigned row = (unsigned)(rA + k);
;             if (EPI == EPI_HID) {
;               *(unsigned*)(ws + O_HID + (row * 1024u + (unsigned)(colp + cc)) * 2u) = pk2(lo[k], hi[k]);
;             } else if (EPI == EPI_COLS) {
;               *(unsigned*)(ws + O_COLS + (row * (unsigned)NCP + (unsigned)(colp + cc)) * 2u) = pk2(lo[k], hi[k]);
	v_mov_b32_dpp v144, v144 quad_perm:[1,0,3,2] row_mask:0xf bank_mask:0xf bound_ctrl:1
	v_mov_b32_dpp v145, v145 quad_perm:[1,0,3,2] row_mask:0xf bank_mask:0xf bound_ctrl:1
	v_mov_b32_dpp v146, v146 quad_perm:[1,0,3,2] row_mask:0xf bank_mask:0xf bound_ctrl:1
	v_cndmask_b32_e32 v92, v143, v92, vcc
	v_cndmask_b32_e32 v94, v94, v143, vcc
	v_cndmask_b32_e32 v93, v144, v93, vcc
	v_cndmask_b32_e32 v95, v95, v144, vcc
	v_cvt_pk_bf16_f32 v92, v92, v94
	v_cvt_pk_bf16_f32 v93, v93, v95
	ds_write_b32 v130, v92 offset:16896
	ds_write_b32 v130, v93 offset:17424
	v_cndmask_b32_e32 v84, v145, v84, vcc
	v_cndmask_b32_e32 v86, v86, v145, vcc
	v_cndmask_b32_e32 v85, v146, v85, vcc
	v_cndmask_b32_e32 v87, v87, v146, vcc
	v_cvt_pk_bf16_f32 v84, v84, v86
	v_cvt_pk_bf16_f32 v85, v85, v87
	ds_write_b32 v130, v84 offset:16928
	ds_write_b32 v130, v85 offset:17456
	v_cndmask_b32_e32 v143, v88, v90, vcc
	v_cndmask_b32_e32 v144, v89, v91, vcc
	v_cndmask_b32_e32 v145, v80, v82, vcc
	v_cndmask_b32_e32 v146, v81, v83, vcc
	v_mov_b32_dpp v143, v143 quad_perm:[1,0,3,2] row_mask:0xf bank_mask:0xf bound_ctrl:1
	v_mov_b32_dpp v144, v144 quad_perm:[1,0,3,2] row_mask:0xf bank_mask:0xf bound_ctrl:1
	v_mov_b32_dpp v145, v145 quad_perm:[1,0,3,2] row_mask:0xf bank_mask:0xf bound_ctrl:1
	v_mov_b32_dpp v146, v146 quad_perm:[1,0,3,2] row_mask:0xf bank_mask:0xf bound_ctrl:1
	v_cndmask_b32_e32 v88, v143, v88, vcc
	v_cndmask_b32_e32 v90, v90, v143, vcc
	v_cndmask_b32_e32 v89, v144, v89, vcc
	v_cndmask_b32_e32 v91, v91, v144, vcc
	v_cvt_pk_bf16_f32 v88, v88, v90
	v_cvt_pk_bf16_f32 v89, v89, v91
	ds_write_b32 v130, v88 offset:17152
	ds_write_b32 v130, v89 offset:17680
	v_cndmask_b32_e32 v80, v145, v80, vcc
	v_cndmask_b32_e32 v82, v82, v145, vcc
	v_cndmask_b32_e32 v81, v146, v81, vcc
	v_cndmask_b32_e32 v83, v83, v146, vcc
	v_cvt_pk_bf16_f32 v80, v80, v82
	v_cvt_pk_bf16_f32 v81, v81, v83
	ds_write_b32 v130, v80 offset:17184
	ds_write_b32 v130, v81 offset:17712
	v_cndmask_b32_e32 v143, v76, v78, vcc
	v_cndmask_b32_e32 v144, v77, v79, vcc
	v_cndmask_b32_e32 v145, v68, v70, vcc
	v_cndmask_b32_e32 v146, v69, v71, vcc
	v_mov_b32_dpp v143, v143 quad_perm:[1,0,3,2] row_mask:0xf bank_mask:0xf bound_ctrl:1
	v_mov_b32_dpp v144, v144 quad_perm:[1,0,3,2] row_mask:0xf bank_mask:0xf bound_ctrl:1
	v_mov_b32_dpp v145, v145 quad_perm:[1,0,3,2] row_mask:0xf bank_mask:0xf bound_ctrl:1
	v_mov_b32_dpp v146, v146 quad_perm:[1,0,3,2] row_mask:0xf bank_mask:0xf bound_ctrl:1
	v_cndmask_b32_e32 v76, v143, v76, vcc
	v_cndmask_b32_e32 v78, v78, v143, vcc
	v_cndmask_b32_e32 v77, v144, v77, vcc
	v_cndmask_b32_e32 v79, v79, v144, vcc
	v_cvt_pk_bf16_f32 v76, v76, v78
	v_cvt_pk_bf16_f32 v77, v77, v79
	ds_write_b32 v130, v76 offset:25344
	ds_write_b32 v130, v77 offset:25872
	v_cndmask_b32_e32 v68, v145, v68, vcc
	v_cndmask_b32_e32 v70, v70, v145, vcc
	v_cndmask_b32_e32 v69, v146, v69, vcc
	v_cndmask_b32_e32 v71, v71, v146, vcc
	v_cvt_pk_bf16_f32 v68, v68, v70
	v_cvt_pk_bf16_f32 v69, v69, v71
	ds_write_b32 v130, v68 offset:25376
	ds_write_b32 v130, v69 offset:25904
	v_cndmask_b32_e32 v143, v72, v74, vcc
	v_cndmask_b32_e32 v144, v73, v75, vcc
	v_cndmask_b32_e32 v145, v60, v62, vcc
	v_cndmask_b32_e32 v146, v61, v63, vcc
	v_mov_b32_dpp v143, v143 quad_perm:[1,0,3,2] row_mask:0xf bank_mask:0xf bound_ctrl:1
	v_mov_b32_dpp v144, v144 quad_perm:[1,0,3,2] row_mask:0xf bank_mask:0xf bound_ctrl:1
	v_mov_b32_dpp v145, v145 quad_perm:[1,0,3,2] row_mask:0xf bank_mask:0xf bound_ctrl:1
	v_mov_b32_dpp v146, v146 quad_perm:[1,0,3,2] row_mask:0xf bank_mask:0xf bound_ctrl:1
	v_cndmask_b32_e32 v72, v143, v72, vcc
	v_cndmask_b32_e32 v74, v74, v143, vcc
	v_cndmask_b32_e32 v73, v144, v73, vcc
	v_cndmask_b32_e32 v75, v75, v144, vcc
	v_cvt_pk_bf16_f32 v72, v72, v74
	v_cvt_pk_bf16_f32 v73, v73, v75
	ds_write_b32 v130, v72 offset:25600
	ds_write_b32 v130, v73 offset:26128
	v_cndmask_b32_e32 v60, v145, v60, vcc
	v_cndmask_b32_e32 v62, v62, v145, vcc
	v_cndmask_b32_e32 v61, v146, v61, vcc
	v_cndmask_b32_e32 v63, v63, v146, vcc
	v_cvt_pk_bf16_f32 v60, v60, v62
	v_cvt_pk_bf16_f32 v61, v61, v63
	ds_write_b32 v130, v60 offset:25632
	ds_write_b32 v130, v61 offset:26160
	v_cndmask_b32_e32 v143, v64, v66, vcc
	v_cndmask_b32_e32 v144, v65, v67, vcc
	v_cndmask_b32_e32 v145, v52, v54, vcc
	v_cndmask_b32_e32 v146, v53, v55, vcc
	v_mov_b32_dpp v143, v143 quad_perm:[1,0,3,2] row_mask:0xf bank_mask:0xf bound_ctrl:1
	v_mov_b32_dpp v144, v144 quad_perm:[1,0,3,2] row_mask:0xf bank_mask:0xf bound_ctrl:1
	v_mov_b32_dpp v145, v145 quad_perm:[1,0,3,2] row_mask:0xf bank_mask:0xf bound_ctrl:1
	v_mov_b32_dpp v146, v146 quad_perm:[1,0,3,2] row_mask:0xf bank_mask:0xf bound_ctrl:1
	v_cndmask_b32_e32 v64, v143, v64, vcc
	v_cndmask_b32_e32 v66, v66, v143, vcc
	v_cndmask_b32_e32 v65, v144, v65, vcc
	v_cndmask_b32_e32 v67, v67, v144, vcc
	v_cvt_pk_bf16_f32 v64, v64, v66
	v_cvt_pk_bf16_f32 v65, v65, v67
	ds_write_b32 v131, v64
	ds_write_b32 v131, v65 offset:528
	v_cndmask_b32_e32 v52, v145, v52, vcc
	v_cndmask_b32_e32 v54, v54, v145, vcc
	v_cndmask_b32_e32 v53, v146, v53, vcc
	v_cndmask_b32_e32 v55, v55, v146, vcc
	v_cvt_pk_bf16_f32 v52, v52, v54
	v_cvt_pk_bf16_f32 v53, v53, v55
	ds_write_b32 v131, v52 offset:32
	ds_write_b32 v131, v53 offset:560
	v_cndmask_b32_e32 v143, v56, v58, vcc
	v_cndmask_b32_e32 v144, v57, v59, vcc
	v_cndmask_b32_e32 v145, v48, v50, vcc
	v_cndmask_b32_e32 v146, v49, v51, vcc
	v_mov_b32_dpp v143, v143 quad_perm:[1,0,3,2] row_mask:0xf bank_mask:0xf bound_ctrl:1
	v_mov_b32_dpp v144, v144 quad_perm:[1,0,3,2] row_mask:0xf bank_mask:0xf bound_ctrl:1
	v_mov_b32_dpp v145, v145 quad_perm:[1,0,3,2] row_mask:0xf bank_mask:0xf bound_ctrl:1
; DEVINL float sigm(float x) { return 1.f / (1.f + __expf(-x)); }
; template <int EPI, bool GATHER>
; DEVINL void gemm_tile(const Params& p, const u16* __restrict__ A, int lda, const int* __restrict__ rowidx,
;                       const u16* __restrict__ Bt, int ldb, int K, int brow, int bcol, int orow, int ocol) {
;     ...
;         for (int n = 0; n < 2; ++n) {
;           const int cc = bj * HALF + n * 16;
;           f32x4 v = acc[ai][bj][m][n];
;           if (EPI == EPI_HID) {
; #pragma unroll
;             for (int j = 0; j < 4; ++j) { const float a1 = acc[ai][0][m][n][j], a3 = acc[ai][1][m][n][j]; v[j] = a1 * sigm(a1) * a3; }
;           }
;           float lo[2], hi[2];
;           xchg_pairs(v, odd, lo, hi);
; #pragma unroll
;           for (int k = 0; k < 2; ++k) {
;             const unsigned row = (unsigned)(rA + k);
;             if (EPI == EPI_HID) {
;               *(unsigned*)(ws + O_HID + (row * 1024u + (unsigned)(colp + cc)) * 2u) = pk2(lo[k], hi[k]);
;             } else if (EPI == EPI_COLS) {
;               *(unsigned*)(ws + O_COLS + (row * (unsigned)NCP + (unsigned)(colp + cc)) * 2u) = pk2(lo[k], hi[k]);
	v_mov_b32_dpp v146, v146 quad_perm:[1,0,3,2] row_mask:0xf bank_mask:0xf bound_ctrl:1
	v_cndmask_b32_e32 v56, v143, v56, vcc
	v_cndmask_b32_e32 v58, v58, v143, vcc
	v_cndmask_b32_e32 v57, v144, v57, vcc
	v_cndmask_b32_e32 v59, v59, v144, vcc
	v_cvt_pk_bf16_f32 v56, v56, v58
	v_cvt_pk_bf16_f32 v57, v57, v59
	ds_write_b32 v131, v56 offset:256
	ds_write_b32 v131, v57 offset:784
	v_cndmask_b32_e32 v48, v145, v48, vcc
	v_cndmask_b32_e32 v50, v50, v145, vcc
	v_cndmask_b32_e32 v49, v146, v49, vcc
	v_cndmask_b32_e32 v51, v51, v146, vcc
	v_cvt_pk_bf16_f32 v48, v48, v50
	v_cvt_pk_bf16_f32 v49, v49, v51
	ds_write_b32 v131, v48 offset:288
	ds_write_b32 v131, v49 offset:816
	v_cndmask_b32_e32 v143, v44, v46, vcc
	v_cndmask_b32_e32 v144, v45, v47, vcc
	v_cndmask_b32_e32 v145, v36, v38, vcc
	v_cndmask_b32_e32 v146, v37, v39, vcc
	v_mov_b32_dpp v143, v143 quad_perm:[1,0,3,2] row_mask:0xf bank_mask:0xf bound_ctrl:1
	v_mov_b32_dpp v144, v144 quad_perm:[1,0,3,2] row_mask:0xf bank_mask:0xf bound_ctrl:1
	v_mov_b32_dpp v145, v145 quad_perm:[1,0,3,2] row_mask:0xf bank_mask:0xf bound_ctrl:1
	v_mov_b32_dpp v146, v146 quad_perm:[1,0,3,2] row_mask:0xf bank_mask:0xf bound_ctrl:1
	v_cndmask_b32_e32 v44, v143, v44, vcc
	v_cndmask_b32_e32 v46, v46, v143, vcc
	v_cndmask_b32_e32 v45, v144, v45, vcc
	v_cndmask_b32_e32 v47, v47, v144, vcc
	v_cvt_pk_bf16_f32 v44, v44, v46
	v_cvt_pk_bf16_f32 v45, v45, v47
	ds_write_b32 v131, v44 offset:8448
	ds_write_b32 v131, v45 offset:8976
	v_cndmask_b32_e32 v36, v145, v36, vcc
	v_cndmask_b32_e32 v38, v38, v145, vcc
	v_cndmask_b32_e32 v37, v146, v37, vcc
	v_cndmask_b32_e32 v39, v39, v146, vcc
	v_cvt_pk_bf16_f32 v36, v36, v38
	v_cvt_pk_bf16_f32 v37, v37, v39
	ds_write_b32 v131, v36 offset:8480
	ds_write_b32 v131, v37 offset:9008
	v_cndmask_b32_e32 v143, v40, v42, vcc
	v_cndmask_b32_e32 v144, v41, v43, vcc
	v_cndmask_b32_e32 v145, v32, v34, vcc
	v_cndmask_b32_e32 v146, v33, v35, vcc
	v_mov_b32_dpp v143, v143 quad_perm:[1,0,3,2] row_mask:0xf bank_mask:0xf bound_ctrl:1
	v_mov_b32_dpp v144, v144 quad_perm:[1,0,3,2] row_mask:0xf bank_mask:0xf bound_ctrl:1
	v_mov_b32_dpp v145, v145 quad_perm:[1,0,3,2] row_mask:0xf bank_mask:0xf bound_ctrl:1
	v_mov_b32_dpp v146, v146 quad_perm:[1,0,3,2] row_mask:0xf bank_mask:0xf bound_ctrl:1
	v_cndmask_b32_e32 v40, v143, v40, vcc
	v_cndmask_b32_e32 v42, v42, v143, vcc
	v_cndmask_b32_e32 v41, v144, v41, vcc
	v_cndmask_b32_e32 v43, v43, v144, vcc
	v_cvt_pk_bf16_f32 v40, v40, v42
	v_cvt_pk_bf16_f32 v41, v41, v43
	ds_write_b32 v131, v40 offset:8704
	ds_write_b32 v131, v41 offset:9232
	v_cndmask_b32_e32 v32, v145, v32, vcc
	v_cndmask_b32_e32 v34, v34, v145, vcc
	v_cndmask_b32_e32 v33, v146, v33, vcc
	v_cndmask_b32_e32 v35, v35, v146, vcc
	v_cvt_pk_bf16_f32 v32, v32, v34
	v_cvt_pk_bf16_f32 v33, v33, v35
	ds_write_b32 v131, v32 offset:8736
	ds_write_b32 v131, v33 offset:9264
	v_cndmask_b32_e32 v143, v28, v30, vcc
	v_cndmask_b32_e32 v144, v29, v31, vcc
	v_cndmask_b32_e32 v145, v20, v22, vcc
	v_cndmask_b32_e32 v146, v21, v23, vcc
	v_mov_b32_dpp v143, v143 quad_perm:[1,0,3,2] row_mask:0xf bank_mask:0xf bound_ctrl:1
	v_mov_b32_dpp v144, v144 quad_perm:[1,0,3,2] row_mask:0xf bank_mask:0xf bound_ctrl:1
	v_mov_b32_dpp v145, v145 quad_perm:[1,0,3,2] row_mask:0xf bank_mask:0xf bound_ctrl:1
	v_mov_b32_dpp v146, v146 quad_perm:[1,0,3,2] row_mask:0xf bank_mask:0xf bound_ctrl:1
	v_cndmask_b32_e32 v28, v143, v28, vcc
	v_cndmask_b32_e32 v30, v30, v143, vcc
	v_cndmask_b32_e32 v29, v144, v29, vcc
	v_cndmask_b32_e32 v31, v31, v144, vcc
	v_cvt_pk_bf16_f32 v28, v28, v30
	v_cvt_pk_bf16_f32 v29, v29, v31
	ds_write_b32 v131, v28 offset:16896
	ds_write_b32 v131, v29 offset:17424
	v_cndmask_b32_e32 v20, v145, v20, vcc
	v_cndmask_b32_e32 v22, v22, v145, vcc
	v_cndmask_b32_e32 v21, v146, v21, vcc
	v_cndmask_b32_e32 v23, v23, v146, vcc
	v_cvt_pk_bf16_f32 v20, v20, v22
	v_cvt_pk_bf16_f32 v21, v21, v23
	ds_write_b32 v131, v20 offset:16928
	ds_write_b32 v131, v21 offset:17456
	v_cndmask_b32_e32 v143, v24, v26, vcc
	v_cndmask_b32_e32 v144, v25, v27, vcc
	v_cndmask_b32_e32 v145, v16, v18, vcc
	v_cndmask_b32_e32 v146, v17, v19, vcc
	v_mov_b32_dpp v143, v143 quad_perm:[1,0,3,2] row_mask:0xf bank_mask:0xf bound_ctrl:1
	v_mov_b32_dpp v144, v144 quad_perm:[1,0,3,2] row_mask:0xf bank_mask:0xf bound_ctrl:1
	v_mov_b32_dpp v145, v145 quad_perm:[1,0,3,2] row_mask:0xf bank_mask:0xf bound_ctrl:1
	v_mov_b32_dpp v146, v146 quad_perm:[1,0,3,2] row_mask:0xf bank_mask:0xf bound_ctrl:1
	v_cndmask_b32_e32 v24, v143, v24, vcc
	v_cndmask_b32_e32 v26, v26, v143, vcc
	v_cndmask_b32_e32 v25, v144, v25, vcc
	v_cndmask_b32_e32 v27, v27, v144, vcc
	v_cvt_pk_bf16_f32 v24, v24, v26
	v_cvt_pk_bf16_f32 v25, v25, v27
	ds_write_b32 v131, v24 offset:17152
	ds_write_b32 v131, v25 offset:17680
	v_cndmask_b32_e32 v16, v145, v16, vcc
; template <int EPI, bool GATHER>
; DEVINL void gemm_tile(const Params& p, const u16* __restrict__ A, int lda, const int* __restrict__ rowidx,
;                       const u16* __restrict__ Bt, int ldb, int K, int brow, int bcol, int orow, int ocol) {
;     ...
;           xchg_pairs(v, odd, lo, hi);
; #pragma unroll
;           for (int k = 0; k < 2; ++k) {
;             const unsigned row = (unsigned)(rA + k);
;             if (EPI == EPI_HID) {
;               *(unsigned*)(ws + O_HID + (row * 1024u + (unsigned)(colp + cc)) * 2u) = pk2(lo[k], hi[k]);
;             } else if (EPI == EPI_COLS) {
;               *(unsigned*)(ws + O_COLS + (row * (unsigned)NCP + (unsigned)(colp + cc)) * 2u) = pk2(lo[k], hi[k]);
; DEVINL void phase1(const Params& p) {
;     ...
;   for (int t = blockIdx.x; t < ntiles; t += gridDim.x) {
;     int pm = t & 31, pn = t >> 5;
;     gemm_tile<EPI_COLS, false>(p, A, 2048, nullptr, Bt, 2048, 2048, pm * 256, pn * 256, pm * 256, pn * 256);
	v_cndmask_b32_e32 v18, v18, v145, vcc
	v_cndmask_b32_e32 v17, v146, v17, vcc
	v_cndmask_b32_e32 v19, v19, v146, vcc
	v_cvt_pk_bf16_f32 v16, v16, v18
	v_cvt_pk_bf16_f32 v17, v17, v19
	ds_write_b32 v131, v16 offset:17184
	ds_write_b32 v131, v17 offset:17712
	v_cndmask_b32_e32 v143, v12, v14, vcc
	v_cndmask_b32_e32 v144, v13, v15, vcc
	v_cndmask_b32_e32 v145, v4, v6, vcc
	v_cndmask_b32_e32 v146, v5, v7, vcc
	v_mov_b32_dpp v143, v143 quad_perm:[1,0,3,2] row_mask:0xf bank_mask:0xf bound_ctrl:1
	v_mov_b32_dpp v144, v144 quad_perm:[1,0,3,2] row_mask:0xf bank_mask:0xf bound_ctrl:1
	v_mov_b32_dpp v145, v145 quad_perm:[1,0,3,2] row_mask:0xf bank_mask:0xf bound_ctrl:1
	v_mov_b32_dpp v146, v146 quad_perm:[1,0,3,2] row_mask:0xf bank_mask:0xf bound_ctrl:1
	v_cndmask_b32_e32 v12, v143, v12, vcc
	v_cndmask_b32_e32 v14, v14, v143, vcc
	v_cndmask_b32_e32 v13, v144, v13, vcc
	v_cndmask_b32_e32 v15, v15, v144, vcc
	v_cvt_pk_bf16_f32 v12, v12, v14
	v_cvt_pk_bf16_f32 v13, v13, v15
	ds_write_b32 v131, v12 offset:25344
	ds_write_b32 v131, v13 offset:25872
	v_cndmask_b32_e32 v4, v145, v4, vcc
	v_cndmask_b32_e32 v6, v6, v145, vcc
	v_cndmask_b32_e32 v5, v146, v5, vcc
	v_cndmask_b32_e32 v7, v7, v146, vcc
	v_cvt_pk_bf16_f32 v4, v4, v6
	v_cvt_pk_bf16_f32 v5, v5, v7
	ds_write_b32 v131, v4 offset:25376
	ds_write_b32 v131, v5 offset:25904
	v_cndmask_b32_e32 v143, v8, v10, vcc
	v_cndmask_b32_e32 v144, v9, v11, vcc
	v_cndmask_b32_e32 v145, v0, v2, vcc
	v_cndmask_b32_e32 v146, v1, v3, vcc
	v_mov_b32_dpp v143, v143 quad_perm:[1,0,3,2] row_mask:0xf bank_mask:0xf bound_ctrl:1
	v_mov_b32_dpp v144, v144 quad_perm:[1,0,3,2] row_mask:0xf bank_mask:0xf bound_ctrl:1
	v_mov_b32_dpp v145, v145 quad_perm:[1,0,3,2] row_mask:0xf bank_mask:0xf bound_ctrl:1
	v_mov_b32_dpp v146, v146 quad_perm:[1,0,3,2] row_mask:0xf bank_mask:0xf bound_ctrl:1
	v_cndmask_b32_e32 v8, v143, v8, vcc
	v_cndmask_b32_e32 v10, v10, v143, vcc
	v_cndmask_b32_e32 v9, v144, v9, vcc
	v_cndmask_b32_e32 v11, v11, v144, vcc
	v_cvt_pk_bf16_f32 v8, v8, v10
	v_cvt_pk_bf16_f32 v9, v9, v11
	ds_write_b32 v131, v8 offset:25600
	ds_write_b32 v131, v9 offset:26128
	v_cndmask_b32_e32 v0, v145, v0, vcc
	v_cndmask_b32_e32 v2, v2, v145, vcc
	v_cndmask_b32_e32 v1, v146, v1, vcc
	v_cndmask_b32_e32 v3, v3, v146, vcc
	v_cvt_pk_bf16_f32 v0, v0, v2
	v_cvt_pk_bf16_f32 v1, v1, v3
	ds_write_b32 v131, v0 offset:25632
	ds_write_b32 v131, v1 offset:26160
	s_waitcnt lgkmcnt(0)
	s_barrier
	ds_read_b128 v[0:3], v132
	ds_read_b128 v[4:7], v132 offset:8448
	ds_read_b128 v[8:11], v132 offset:16896
	ds_read_b128 v[12:15], v132 offset:25344
	ds_read_b128 v[16:19], v132 offset:33792
	ds_read_b128 v[20:23], v132 offset:42240
	ds_read_b128 v[24:27], v132 offset:50688
	ds_read_b128 v[28:31], v132 offset:59136
	ds_read_b128 v[32:35], v133
	ds_read_b128 v[36:39], v133 offset:8448
	ds_read_b128 v[40:43], v133 offset:16896
	ds_read_b128 v[44:47], v133 offset:25344
	ds_read_b128 v[48:51], v133 offset:33792
	ds_read_b128 v[52:55], v133 offset:42240
	ds_read_b128 v[56:59], v133 offset:50688
	ds_read_b128 v[60:63], v133 offset:59136
	v_add_u32_e32 v65, 0x54000, v134
	v_add_u32_e32 v66, 0xa8000, v134
	v_add_u32_e32 v67, 0xfc000, v134
	v_add_u32_e32 v68, 0x150000, v134
	v_add_u32_e32 v69, 0x1a4000, v134
	v_add_u32_e32 v70, 0x1f8000, v134
	v_add_u32_e32 v71, 0x24c000, v134
	v_add_u32_e32 v72, 0x2a0000, v134
	v_add_u32_e32 v73, 0x2f4000, v134
	v_add_u32_e32 v74, 0x348000, v134
	v_add_u32_e32 v75, 0x39c000, v134
	v_add_u32_e32 v76, 0x3f0000, v134
	v_add_u32_e32 v77, 0x444000, v134
	v_add_u32_e32 v78, 0x498000, v134
	v_add_u32_e32 v79, 0x4ec000, v134
	s_waitcnt lgkmcnt(15)
	global_store_dwordx4 v134, v[0:3], s[0:1]
	s_waitcnt lgkmcnt(14)
	global_store_dwordx4 v65, v[4:7], s[0:1]
	s_waitcnt lgkmcnt(13)
	global_store_dwordx4 v66, v[8:11], s[0:1]
	s_waitcnt lgkmcnt(12)
	global_store_dwordx4 v67, v[12:15], s[0:1]
	s_waitcnt lgkmcnt(11)
	global_store_dwordx4 v68, v[16:19], s[0:1]
	s_waitcnt lgkmcnt(10)
	global_store_dwordx4 v69, v[20:23], s[0:1]
	s_waitcnt lgkmcnt(9)
	global_store_dwordx4 v70, v[24:27], s[0:1]
	s_waitcnt lgkmcnt(8)
	global_store_dwordx4 v71, v[28:31], s[0:1]
	s_waitcnt lgkmcnt(7)
	global_store_dwordx4 v72, v[32:35], s[0:1]
	s_waitcnt lgkmcnt(6)
	global_store_dwordx4 v73, v[36:39], s[0:1]
	s_waitcnt lgkmcnt(5)
	global_store_dwordx4 v74, v[40:43], s[0:1]
	s_waitcnt lgkmcnt(4)
	global_store_dwordx4 v75, v[44:47], s[0:1]
	s_waitcnt lgkmcnt(3)
	global_store_dwordx4 v76, v[48:51], s[0:1]
	s_waitcnt lgkmcnt(2)
	global_store_dwordx4 v77, v[52:55], s[0:1]
	s_waitcnt lgkmcnt(1)
	global_store_dwordx4 v78, v[56:59], s[0:1]
	s_waitcnt lgkmcnt(0)
	global_store_dwordx4 v79, v[60:63], s[0:1]
	s_add_i32 s47, s47, s94
	s_add_i32 s3, s3, s40
	s_add_i32 s41, s41, s42
	s_cmpk_lt_i32 s47, 0x500
	s_nop 0
	s_barrier
	s_cbranch_scc0 .LBB0_230
